# diff attention: 4-slot K/V ring, workgroup barrier (with vmcnt(0)) only after every second tile
# speedup vs baseline: 1.0026x; 1.0026x over previous
.LBB0_97:
	s_bfe_u32 s10, s48, 0x10007
	s_add_i32 s10, s48, s10
	s_bfe_i32 s10, s10, 0x80000
	s_sext_i32_i16 s10, s10
	s_ashr_i32 s10, s10, 1
	s_mul_hi_i32 s11, s10, 0x880000
	s_mul_i32 s10, s10, 0x880000
	s_add_u32 s39, s0, s10
	s_addc_u32 s42, s1, s11
	s_ashr_i32 s47, s46, 31
	s_lshl_b64 s[10:11], s[46:47], 1
	s_add_u32 s44, s39, s10
	v_cndmask_b32_e64 v1, 0, 1, s[28:29]
	s_addc_u32 s45, s42, s11
	v_cmp_ne_u32_e64 s[10:11], 1, v1
	s_andn2_b64 vcc, exec, s[28:29]
	s_cbranch_vccnz .LBB0_126
	s_add_i32 s12, s41, 0
	v_lshl_add_u64 v[2:3], s[44:45], 0, v[150:151]
	s_add_i32 m0, s12, 0x9000
	s_nop 0
	global_load_lds_dwordx4 v[2:3], off
	v_cndmask_b32_e64 v1, 0, 1, s[34:35]
	v_cmp_ne_u32_e64 s[12:13], 1, v1
	s_andn2_b64 vcc, exec, s[34:35]
	s_cbranch_vccz .LBB0_127

.LBB0_100:
	s_add_i32 s30, s41, 0
	v_lshl_add_u64 v[2:3], s[44:45], 0, v[146:147]
	s_add_i32 m0, s30, 0xd000
	s_nop 0
	global_load_lds_dwordx4 v[2:3], off
	s_and_b64 vcc, exec, s[6:7]
	s_add_i32 s44, s49, 0x8040
	s_cbranch_vccz .LBB0_129

.LBB0_102:
	s_ashr_i32 s45, s44, 31
	s_lshl_b64 s[30:31], s[44:45], 1
	s_add_u32 s44, s39, s30
	s_addc_u32 s45, s42, s31
	s_and_b64 vcc, exec, s[10:11]
	s_cbranch_vccnz .LBB0_131
	s_add_i32 s30, s41, 0
	v_lshl_add_u64 v[2:3], s[44:45], 0, v[150:151]
	s_add_i32 m0, s30, 0xd800
	s_nop 0
	global_load_lds_dwordx4 v[2:3], off
	s_and_b64 vcc, exec, s[12:13]
	s_cbranch_vccz .LBB0_132

.LBB0_105:
	s_add_i32 s30, s41, 0
	v_lshl_add_u64 v[2:3], s[44:45], 0, v[146:147]
	s_add_i32 m0, s30, 0x11800
	s_nop 0
	global_load_lds_dwordx4 v[2:3], off

.Latt_diff_p0:
.LBB0_107:
.LBB0_116:
	ds_read_b128 v[112:115], v242 offset:0
	ds_read_b128 v[116:119], v242 offset:32
	ds_read_b128 v[120:123], v242 offset:64
	ds_read_b128 v[124:127], v242 offset:96
	s_add_i32 s30, s52, 2
	s_cmp_ge_u32 s30, s21
	s_cselect_b64 s[46:47], -1, 0
	s_cbranch_scc1 .Latt_diff_dmaend
	s_cmp_lt_u32 s52, 2
	s_cselect_b32 s48, s45, s43
	s_mul_i32 s55, s50, 0x2400
	s_add_i32 s56, s55, s41
	s_mov_b32 m0, s56
	v_lshl_add_u32 v244, s48, 12, v153
	global_load_lds_dwordx4 v244, s[18:19]
	s_ashr_i32 s49, s48, 31
	s_lshl_b64 s[30:31], s[48:49], 1
	s_add_i32 s55, s55, s56
	s_add_i32 m0, s55, 0x9000
	s_add_u32 s30, s39, s30
	s_addc_u32 s31, s42, s31
	global_load_lds_dwordx4 v150, s[30:31]
	s_add_i32 m0, s55, 0xb000
	s_and_b64 vcc, exec, s[14:15]
	global_load_lds_dwordx4 v148, s[30:31]
	s_cbranch_vccz .Latt_diff_dmax
.Latt_diff_dmaend:
	s_waitcnt lgkmcnt(2)
	v_mfma_f32_32x32x16_bf16 v[64:79], v[112:115], v[130:133], v[96:111]
	ds_read_b128 v[112:115], v242 offset:4608
	v_mfma_f32_32x32x16_bf16 v[64:79], v[116:119], v[134:137], v[64:79]
	ds_read_b128 v[116:119], v242 offset:4640
	s_waitcnt lgkmcnt(2)
	v_mfma_f32_32x32x16_bf16 v[64:79], v[120:123], v[138:141], v[64:79]
	ds_read_b128 v[120:123], v242 offset:4672
	v_mfma_f32_32x32x16_bf16 v[64:79], v[124:127], v[142:145], v[64:79]
	ds_read_b128 v[124:127], v242 offset:4704
	s_waitcnt lgkmcnt(2)
	v_mfma_f32_32x32x16_bf16 v[80:95], v[112:115], v[130:133], v[96:111]
	v_mfma_f32_32x32x16_bf16 v[80:95], v[116:119], v[134:137], v[80:95]
	s_waitcnt lgkmcnt(0)
	v_mfma_f32_32x32x16_bf16 v[80:95], v[120:123], v[138:141], v[80:95]
	v_mfma_f32_32x32x16_bf16 v[80:95], v[124:127], v[142:145], v[80:95]
	ds_read_b128 v[112:115], v243 offset:36864
	ds_read_b128 v[116:119], v243 offset:41472
	ds_read_b128 v[120:123], v243 offset:46080
	ds_read_b128 v[124:127], v243 offset:50688
	s_cmp_eq_u32 s52, 0
	s_cselect_b32 s31, 0xff7fffff, 0
	v_max3_f32 v227, v64, v65, v66
	v_max3_f32 v228, v67, v68, v69
	v_max3_f32 v227, v227, v70, v71
	v_max3_f32 v228, v228, v72, v73
	v_max3_f32 v227, v227, v74, v75
	v_max3_f32 v228, v228, v76, v77
	v_max3_f32 v227, v227, v78, v79
	v_max3_f32 v229, v80, v81, v82
	v_max3_f32 v226, v83, v84, v85
	v_max3_f32 v229, v229, v86, v87
	v_max3_f32 v226, v226, v88, v89
	v_max3_f32 v229, v229, v90, v91
	v_max3_f32 v226, v226, v92, v93
	v_max3_f32 v229, v229, v94, v95
	v_max3_f32 v226, v226, v227, v228
	v_max_f32_e32 v226, v226, v229
	v_cmp_lt_f32_e32 vcc, s58, v226
	s_cmp_eq_u32 s52, 0
	s_cbranch_scc1 .Latt_diff_rare
	s_cbranch_vccnz .Latt_diff_rare
.Latt_diff_norescale:
	v_exp_f32_e32 v64, v64
	v_exp_f32_e32 v65, v65
	v_exp_f32_e32 v66, v66
	v_exp_f32_e32 v67, v67
	v_exp_f32_e32 v68, v68
	v_exp_f32_e32 v69, v69
	v_exp_f32_e32 v70, v70
	v_exp_f32_e32 v71, v71
	v_cvt_pk_bf16_f32 v218, v64, v65
	v_cvt_pk_bf16_f32 v219, v66, v67
	v_cvt_pk_bf16_f32 v220, v68, v69
	v_cvt_pk_bf16_f32 v221, v70, v71
	s_waitcnt lgkmcnt(2)
	s_nop 0
	v_mfma_f32_32x32x16_bf16 v[0:15], v[112:115], v[218:221], v[0:15]
	ds_read_b128 v[112:115], v243 offset:36896
	v_exp_f32_e32 v72, v72
	v_exp_f32_e32 v73, v73
	v_exp_f32_e32 v74, v74
	v_exp_f32_e32 v75, v75
	v_mfma_f32_32x32x16_bf16 v[48:63], v[116:119], v[218:221], v[48:63]
	ds_read_b128 v[116:119], v243 offset:41504
	v_cvt_pk_bf16_f32 v222, v72, v73
	v_exp_f32_e32 v76, v76
	v_exp_f32_e32 v77, v77
	v_cvt_pk_bf16_f32 v223, v74, v75
	s_waitcnt lgkmcnt(2)
	v_mfma_f32_32x32x16_bf16 v[32:47], v[120:123], v[218:221], v[32:47]
	ds_read_b128 v[120:123], v243 offset:46112
	v_exp_f32_e32 v78, v78
	v_exp_f32_e32 v79, v79
	v_cvt_pk_bf16_f32 v224, v76, v77
	v_cvt_pk_bf16_f32 v225, v78, v79
	v_mfma_f32_32x32x16_bf16 v[16:31], v[124:127], v[218:221], v[16:31]
	ds_read_b128 v[124:127], v243 offset:50720
	v_add_f32_e32 v226, v64, v68
	v_add_f32_e32 v227, v65, v69
	v_add_f32_e32 v228, v66, v70
	v_add_f32_e32 v229, v67, v71
	s_waitcnt lgkmcnt(2)
	v_mfma_f32_32x32x16_bf16 v[0:15], v[112:115], v[222:225], v[0:15]
	ds_read_b128 v[112:115], v243 offset:36928
	v_exp_f32_e32 v80, v80
	v_exp_f32_e32 v81, v81
	v_exp_f32_e32 v82, v82
	v_exp_f32_e32 v83, v83
	v_cvt_pk_bf16_f32 v218, v80, v81
	v_mfma_f32_32x32x16_bf16 v[48:63], v[116:119], v[222:225], v[48:63]
	ds_read_b128 v[116:119], v243 offset:41536
	v_exp_f32_e32 v84, v84
	v_exp_f32_e32 v85, v85
	v_cvt_pk_bf16_f32 v219, v82, v83
	v_exp_f32_e32 v86, v86
	v_exp_f32_e32 v87, v87
	s_waitcnt lgkmcnt(2)
	v_mfma_f32_32x32x16_bf16 v[32:47], v[120:123], v[222:225], v[32:47]
	ds_read_b128 v[120:123], v243 offset:46144
	v_cvt_pk_bf16_f32 v220, v84, v85
	v_cvt_pk_bf16_f32 v221, v86, v87
	v_add_f32_e32 v226, v226, v72
	v_add_f32_e32 v227, v227, v73
	v_add_f32_e32 v228, v228, v74
	v_mfma_f32_32x32x16_bf16 v[16:31], v[124:127], v[222:225], v[16:31]
	ds_read_b128 v[124:127], v243 offset:50752
	v_add_f32_e32 v229, v229, v75
	v_add_f32_e32 v226, v226, v76
	v_add_f32_e32 v227, v227, v77
	v_add_f32_e32 v228, v228, v78
	v_add_f32_e32 v229, v229, v79
	s_waitcnt lgkmcnt(2)
	v_mfma_f32_32x32x16_bf16 v[0:15], v[112:115], v[218:221], v[0:15]
	ds_read_b128 v[112:115], v243 offset:36960
	v_exp_f32_e32 v88, v88
	v_exp_f32_e32 v89, v89
	v_exp_f32_e32 v90, v90
	v_exp_f32_e32 v91, v91
	v_cvt_pk_bf16_f32 v222, v88, v89
	v_mfma_f32_32x32x16_bf16 v[48:63], v[116:119], v[218:221], v[48:63]
	ds_read_b128 v[116:119], v243 offset:41568
	v_exp_f32_e32 v92, v92
	v_exp_f32_e32 v93, v93
	v_cvt_pk_bf16_f32 v223, v90, v91
	v_exp_f32_e32 v94, v94
	v_exp_f32_e32 v95, v95
	s_waitcnt lgkmcnt(2)
	v_mfma_f32_32x32x16_bf16 v[32:47], v[120:123], v[218:221], v[32:47]
	ds_read_b128 v[120:123], v243 offset:46176
	v_cvt_pk_bf16_f32 v224, v92, v93
	v_cvt_pk_bf16_f32 v225, v94, v95
	v_add_f32_e32 v226, v226, v80
	v_add_f32_e32 v227, v227, v81
	v_add_f32_e32 v228, v228, v82
	v_mfma_f32_32x32x16_bf16 v[16:31], v[124:127], v[218:221], v[16:31]
	ds_read_b128 v[124:127], v243 offset:50784
	v_add_f32_e32 v229, v229, v83
	v_add_f32_e32 v226, v226, v84
	v_add_f32_e32 v227, v227, v85
	v_add_f32_e32 v228, v228, v86
	v_add_f32_e32 v229, v229, v87
	s_waitcnt lgkmcnt(2)
	v_mfma_f32_32x32x16_bf16 v[0:15], v[112:115], v[222:225], v[0:15]
	v_add_f32_e32 v226, v226, v88
	v_add_f32_e32 v227, v227, v89
	v_mfma_f32_32x32x16_bf16 v[48:63], v[116:119], v[222:225], v[48:63]
	v_add_f32_e32 v228, v228, v90
	v_add_f32_e32 v229, v229, v91
	s_waitcnt lgkmcnt(0)
	v_mfma_f32_32x32x16_bf16 v[32:47], v[120:123], v[222:225], v[32:47]
	v_add_f32_e32 v226, v226, v92
	v_add_f32_e32 v227, v227, v93
	v_mfma_f32_32x32x16_bf16 v[16:31], v[124:127], v[222:225], v[16:31]
	v_add_f32_e32 v228, v228, v94
	v_add_f32_e32 v229, v229, v95
	v_add_f32_e32 v226, v226, v227
	v_add_f32_e32 v228, v228, v229
	v_add_f32_e32 v226, v226, v228
	v_add_f32_e32 v157, v157, v226
.Latt_diff_skip:
	s_add_i32 s30, s50, 1
	s_and_b32 s46, s30, 3
	s_add_i32 s52, s52, 1
	s_add_i32 s43, s43, 64
	s_add_i32 s45, s45, 64
	s_mov_b32 s53, s51
	s_mov_b32 s51, s50
	s_mov_b32 s50, s46
	s_mul_i32 s30, s53, 0x2400
	v_add_u32_e32 v242, s30, v173
	s_mul_i32 s30, s53, 0x4800
	v_add_u32_e32 v243, s30, v174
	s_bitcmp1_b32 s52, 0
	s_cbranch_scc0 .Latt_diff_nb
	s_waitcnt vmcnt(0) lgkmcnt(0)
	s_barrier
.Latt_diff_nb:
	s_cmp_eq_u32 s21, s52
	s_cbranch_scc0 .LBB0_107
	s_waitcnt vmcnt(0) lgkmcnt(0)
	s_barrier
	s_branch .LBB0_88
.Latt_diff_dmax:
	s_add_i32 m0, s55, 0xd000
	s_and_b64 vcc, exec, s[8:9]
	global_load_lds_dwordx4 v146, s[30:31]
	s_cbranch_vccnz .Latt_diff_dmaend
	s_add_i32 m0, s56, 0x2000
	v_lshl_add_u32 v244, s48, 12, v155
	global_load_lds_dwordx4 v244, s[18:19]
	s_branch .Latt_diff_dmaend

.LBB0_127:
	s_add_i32 s14, s41, 0
	v_lshl_add_u64 v[2:3], s[44:45], 0, v[148:149]
	s_add_i32 m0, s14, 0xb000
	s_nop 0
	global_load_lds_dwordx4 v[2:3], off
	v_cndmask_b32_e64 v1, 0, 1, s[36:37]
	v_cmp_ne_u32_e64 s[14:15], 1, v1
	s_andn2_b64 vcc, exec, s[36:37]
	s_cbranch_vccz .LBB0_100

.LBB0_132:
	s_add_i32 s30, s41, 0
	v_lshl_add_u64 v[2:3], s[44:45], 0, v[148:149]
	s_add_i32 m0, s30, 0xf800
	s_nop 0
	global_load_lds_dwordx4 v[2:3], off
	s_and_b64 vcc, exec, s[14:15]
	s_cbranch_vccz .LBB0_105
	s_branch .LBB0_106
